# FFN-up conv/SiLU epilogue: one store address per 8-row iteration (row r = immediate offset 128*r, next-tile select on wrap) instead of 7 VALU per row
# speedup vs baseline: 1.0087x; 1.0087x over previous
.Lcv5_loop:
	ds_read_b32 v188, v17
	ds_read_b32 v196, v17 offset:256
	ds_read_b32 v189, v17 offset:516
	ds_read_b32 v197, v17 offset:772
	ds_read_b32 v190, v17 offset:1032
	ds_read_b32 v198, v17 offset:1288
	ds_read_b32 v191, v17 offset:1548
	ds_read_b32 v199, v17 offset:1804
	ds_read_b32 v192, v17 offset:2064
	ds_read_b32 v200, v17 offset:2320
	ds_read_b32 v193, v17 offset:2580
	ds_read_b32 v201, v17 offset:2836
	ds_read_b32 v194, v17 offset:3096
	ds_read_b32 v202, v17 offset:3352
	ds_read_b32 v195, v17 offset:3612
	ds_read_b32 v203, v17 offset:3868
	v_add_u32_e32 v32, s63, v18
	v_ashrrev_i32_e32 v220, 7, v32
	v_and_b32_e32 v24, 0x7f, v32
	v_mad_u32_u24 v220, v220, 44, s14
	v_subrev_u32_e32 v33, 64, v24
	v_lshlrev_b32_e32 v24, 7, v24
	v_sub_u32_e32 v34, v40, v32
	v_lshl_or_b32 v24, v220, 14, v24
	v_add_u32_e32 v24, v24, v41
	v_add_u32_e32 v35, 0xac000, v24
	v_cmp_le_i32_e64 s[6:7], 63, v33
	v_cmp_le_i32_e64 s[8:9], 62, v33
	v_cmp_le_i32_e64 vcc, 61, v33
	v_cndmask_b32_e64 v25, v24, v35, s[6:7]
	v_cmp_le_i32_e64 s[6:7], 60, v33
	v_cndmask_b32_e64 v26, v24, v35, s[8:9]
	v_cmp_le_i32_e64 s[8:9], 59, v33
	v_cndmask_b32_e64 v27, v24, v35, vcc
	v_cmp_le_i32_e64 vcc, 58, v33
	v_cndmask_b32_e64 v28, v24, v35, s[6:7]
	v_cmp_le_i32_e64 s[6:7], 57, v33
	v_cndmask_b32_e64 v29, v24, v35, s[8:9]
	v_cndmask_b32_e64 v30, v24, v35, vcc
	s_nop 0
	v_cndmask_b32_e64 v31, v24, v35, s[6:7]
	s_waitcnt lgkmcnt(0)
	v_fma_f32 v204, v3, v15, v9
	v_fma_f32 v212, v2, v14, v8
	v_fma_f32 v205, v3, v10, v9
	v_fma_f32 v213, v2, v11, v8
	v_fma_f32 v206, v3, v188, v9
	v_fma_f32 v214, v2, v196, v8
	v_fma_f32 v207, v3, v189, v9
	v_fma_f32 v215, v2, v197, v8
	v_fma_f32 v208, v3, v190, v9
	v_fma_f32 v216, v2, v198, v8
	v_fma_f32 v209, v3, v191, v9
	v_fma_f32 v217, v2, v199, v8
	v_fma_f32 v210, v3, v192, v9
	v_fma_f32 v218, v2, v200, v8
	v_fma_f32 v211, v3, v193, v9
	v_fma_f32 v219, v2, v201, v8
	v_fma_f32 v204, v5, v10, v204
	v_fma_f32 v212, v4, v11, v212
	v_fma_f32 v205, v5, v188, v205
	v_fma_f32 v213, v4, v196, v213
	v_fma_f32 v206, v5, v189, v206
	v_fma_f32 v214, v4, v197, v214
	v_fma_f32 v207, v5, v190, v207
	v_fma_f32 v215, v4, v198, v215
	v_fma_f32 v208, v5, v191, v208
	v_fma_f32 v216, v4, v199, v216
	v_fma_f32 v209, v5, v192, v209
	v_fma_f32 v217, v4, v200, v217
	v_fma_f32 v210, v5, v193, v210
	v_fma_f32 v218, v4, v201, v218
	v_fma_f32 v211, v5, v194, v211
	v_fma_f32 v219, v4, v202, v219
	v_fma_f32 v204, v7, v188, v204
	v_fma_f32 v212, v6, v196, v212
	v_fma_f32 v205, v7, v189, v205
	v_fma_f32 v213, v6, v197, v213
	v_fma_f32 v206, v7, v190, v206
	v_fma_f32 v214, v6, v198, v214
	v_fma_f32 v207, v7, v191, v207
	v_fma_f32 v215, v6, v199, v215
	v_fma_f32 v208, v7, v192, v208
	v_fma_f32 v216, v6, v200, v216
	v_fma_f32 v209, v7, v193, v209
	v_fma_f32 v217, v6, v201, v217
	v_fma_f32 v210, v7, v194, v210
	v_fma_f32 v218, v6, v202, v218
	v_fma_f32 v211, v7, v195, v211
	v_fma_f32 v219, v6, v203, v219
	v_mul_f32_e32 v220, 0xbfb8aa3b, v204
	v_mul_f32_e32 v221, 0xbfb8aa3b, v205
	v_mul_f32_e32 v222, 0xbfb8aa3b, v206
	v_mul_f32_e32 v223, 0xbfb8aa3b, v207
	v_mul_f32_e32 v224, 0xbfb8aa3b, v208
	v_mul_f32_e32 v225, 0xbfb8aa3b, v209
	v_mul_f32_e32 v226, 0xbfb8aa3b, v210
	v_mul_f32_e32 v227, 0xbfb8aa3b, v211
	v_exp_f32_e32 v220, v220
	v_exp_f32_e32 v221, v221
	v_exp_f32_e32 v222, v222
	v_exp_f32_e32 v223, v223
	v_exp_f32_e32 v224, v224
	v_exp_f32_e32 v225, v225
	v_exp_f32_e32 v226, v226
	v_exp_f32_e32 v227, v227
	v_add_f32_e32 v220, 1.0, v220
	v_add_f32_e32 v221, 1.0, v221
	v_add_f32_e32 v222, 1.0, v222
	v_add_f32_e32 v223, 1.0, v223
	v_add_f32_e32 v224, 1.0, v224
	v_add_f32_e32 v225, 1.0, v225
	v_add_f32_e32 v226, 1.0, v226
	v_add_f32_e32 v227, 1.0, v227
	v_rcp_f32_e32 v220, v220
	v_rcp_f32_e32 v221, v221
	v_rcp_f32_e32 v222, v222
	v_rcp_f32_e32 v223, v223
	v_rcp_f32_e32 v224, v224
	v_rcp_f32_e32 v225, v225
	v_rcp_f32_e32 v226, v226
	v_rcp_f32_e32 v227, v227
	v_mov_b32_e32 v15, v194
	v_mov_b32_e32 v10, v195
	v_mov_b32_e32 v14, v202
	v_mov_b32_e32 v11, v203
	v_mul_f32_e32 v204, v204, v220
	v_mul_f32_e32 v205, v205, v221
	v_mul_f32_e32 v206, v206, v222
	v_mul_f32_e32 v207, v207, v223
	v_mul_f32_e32 v208, v208, v224
	v_mul_f32_e32 v209, v209, v225
	v_mul_f32_e32 v210, v210, v226
	v_mul_f32_e32 v211, v211, v227
	v_mul_f32_e32 v212, v212, v204
	v_mul_f32_e32 v213, v213, v205
	v_mul_f32_e32 v214, v214, v206
	v_mul_f32_e32 v215, v215, v207
	v_mul_f32_e32 v216, v216, v208
	v_mul_f32_e32 v217, v217, v209
	v_mul_f32_e32 v218, v218, v210
	v_mul_f32_e32 v219, v219, v211
	v_cvt_pk_bf16_f32 v212, v212, v212
	v_cvt_pk_bf16_f32 v213, v213, v213
	v_cvt_pk_bf16_f32 v214, v214, v214
	v_cvt_pk_bf16_f32 v215, v215, v215
	v_cvt_pk_bf16_f32 v216, v216, v216
	v_cvt_pk_bf16_f32 v217, v217, v217
	v_cvt_pk_bf16_f32 v218, v218, v218
	v_cvt_pk_bf16_f32 v219, v219, v219
	v_cmp_lt_i32_e32 vcc, 0, v34
	s_and_b64 exec, exec, vcc
	global_store_short v24, v212, s[42:43]
	v_cmp_lt_i32_e32 vcc, 1, v34
	s_and_b64 exec, exec, vcc
	global_store_short v25, v213, s[42:43] offset:128
	v_cmp_lt_i32_e32 vcc, 2, v34
	s_and_b64 exec, exec, vcc
	global_store_short v26, v214, s[42:43] offset:256
	v_cmp_lt_i32_e32 vcc, 3, v34
	s_and_b64 exec, exec, vcc
	global_store_short v27, v215, s[42:43] offset:384
	v_cmp_lt_i32_e32 vcc, 4, v34
	s_and_b64 exec, exec, vcc
	global_store_short v28, v216, s[42:43] offset:512
	v_cmp_lt_i32_e32 vcc, 5, v34
	s_and_b64 exec, exec, vcc
	global_store_short v29, v217, s[42:43] offset:640
	v_cmp_lt_i32_e32 vcc, 6, v34
	s_and_b64 exec, exec, vcc
	global_store_short v30, v218, s[42:43] offset:768
	v_cmp_lt_i32_e32 vcc, 7, v34
	s_and_b64 exec, exec, vcc
	global_store_short v31, v219, s[42:43] offset:896
	s_mov_b64 exec, -1
	v_add_u32_e32 v17, 0x1020, v17
	v_add_u32_e32 v18, 8, v18
	s_sub_u32 s62, s62, 1
	s_cmp_lg_u32 s62, 0
	s_cbranch_scc1 .Lcv5_loop
	s_branch .LBB0_646

.Lcv12_loop:
	ds_read_b32 v188, v17
	ds_read_b32 v196, v17 offset:256
	ds_read_b32 v189, v17 offset:516
	ds_read_b32 v197, v17 offset:772
	ds_read_b32 v190, v17 offset:1032
	ds_read_b32 v198, v17 offset:1288
	ds_read_b32 v191, v17 offset:1548
	ds_read_b32 v199, v17 offset:1804
	ds_read_b32 v192, v17 offset:2064
	ds_read_b32 v200, v17 offset:2320
	ds_read_b32 v193, v17 offset:2580
	ds_read_b32 v201, v17 offset:2836
	ds_read_b32 v194, v17 offset:3096
	ds_read_b32 v202, v17 offset:3352
	ds_read_b32 v195, v17 offset:3612
	ds_read_b32 v203, v17 offset:3868
	v_add_u32_e32 v32, s63, v18
	v_ashrrev_i32_e32 v220, 7, v32
	v_and_b32_e32 v24, 0x7f, v32
	v_mad_u32_u24 v220, v220, 44, s18
	v_subrev_u32_e32 v33, 64, v24
	v_lshlrev_b32_e32 v24, 7, v24
	v_sub_u32_e32 v34, v40, v32
	v_lshl_or_b32 v24, v220, 14, v24
	v_add_u32_e32 v24, v24, v41
	v_add_u32_e32 v35, 0xac000, v24
	v_cmp_le_i32_e64 s[6:7], 63, v33
	v_cmp_le_i32_e64 s[8:9], 62, v33
	v_cmp_le_i32_e64 vcc, 61, v33
	v_cndmask_b32_e64 v25, v24, v35, s[6:7]
	v_cmp_le_i32_e64 s[6:7], 60, v33
	v_cndmask_b32_e64 v26, v24, v35, s[8:9]
	v_cmp_le_i32_e64 s[8:9], 59, v33
	v_cndmask_b32_e64 v27, v24, v35, vcc
	v_cmp_le_i32_e64 vcc, 58, v33
	v_cndmask_b32_e64 v28, v24, v35, s[6:7]
	v_cmp_le_i32_e64 s[6:7], 57, v33
	v_cndmask_b32_e64 v29, v24, v35, s[8:9]
	v_cndmask_b32_e64 v30, v24, v35, vcc
	s_nop 0
	v_cndmask_b32_e64 v31, v24, v35, s[6:7]
	s_waitcnt lgkmcnt(0)
	v_fma_f32 v204, v3, v15, v9
	v_fma_f32 v212, v2, v14, v8
	v_fma_f32 v205, v3, v10, v9
	v_fma_f32 v213, v2, v11, v8
	v_fma_f32 v206, v3, v188, v9
	v_fma_f32 v214, v2, v196, v8
	v_fma_f32 v207, v3, v189, v9
	v_fma_f32 v215, v2, v197, v8
	v_fma_f32 v208, v3, v190, v9
	v_fma_f32 v216, v2, v198, v8
	v_fma_f32 v209, v3, v191, v9
	v_fma_f32 v217, v2, v199, v8
	v_fma_f32 v210, v3, v192, v9
	v_fma_f32 v218, v2, v200, v8
	v_fma_f32 v211, v3, v193, v9
	v_fma_f32 v219, v2, v201, v8
	v_fma_f32 v204, v5, v10, v204
	v_fma_f32 v212, v4, v11, v212
	v_fma_f32 v205, v5, v188, v205
	v_fma_f32 v213, v4, v196, v213
	v_fma_f32 v206, v5, v189, v206
	v_fma_f32 v214, v4, v197, v214
	v_fma_f32 v207, v5, v190, v207
	v_fma_f32 v215, v4, v198, v215
	v_fma_f32 v208, v5, v191, v208
	v_fma_f32 v216, v4, v199, v216
	v_fma_f32 v209, v5, v192, v209
	v_fma_f32 v217, v4, v200, v217
	v_fma_f32 v210, v5, v193, v210
	v_fma_f32 v218, v4, v201, v218
	v_fma_f32 v211, v5, v194, v211
	v_fma_f32 v219, v4, v202, v219
	v_fma_f32 v204, v7, v188, v204
	v_fma_f32 v212, v6, v196, v212
	v_fma_f32 v205, v7, v189, v205
	v_fma_f32 v213, v6, v197, v213
	v_fma_f32 v206, v7, v190, v206
	v_fma_f32 v214, v6, v198, v214
	v_fma_f32 v207, v7, v191, v207
	v_fma_f32 v215, v6, v199, v215
	v_fma_f32 v208, v7, v192, v208
	v_fma_f32 v216, v6, v200, v216
	v_fma_f32 v209, v7, v193, v209
	v_fma_f32 v217, v6, v201, v217
	v_fma_f32 v210, v7, v194, v210
	v_fma_f32 v218, v6, v202, v218
	v_fma_f32 v211, v7, v195, v211
	v_fma_f32 v219, v6, v203, v219
	v_mul_f32_e32 v220, 0xbfb8aa3b, v204
	v_mul_f32_e32 v221, 0xbfb8aa3b, v205
	v_mul_f32_e32 v222, 0xbfb8aa3b, v206
	v_mul_f32_e32 v223, 0xbfb8aa3b, v207
	v_mul_f32_e32 v224, 0xbfb8aa3b, v208
	v_mul_f32_e32 v225, 0xbfb8aa3b, v209
	v_mul_f32_e32 v226, 0xbfb8aa3b, v210
	v_mul_f32_e32 v227, 0xbfb8aa3b, v211
	v_exp_f32_e32 v220, v220
	v_exp_f32_e32 v221, v221
	v_exp_f32_e32 v222, v222
	v_exp_f32_e32 v223, v223
	v_exp_f32_e32 v224, v224
	v_exp_f32_e32 v225, v225
	v_exp_f32_e32 v226, v226
	v_exp_f32_e32 v227, v227
	v_add_f32_e32 v220, 1.0, v220
	v_add_f32_e32 v221, 1.0, v221
	v_add_f32_e32 v222, 1.0, v222
	v_add_f32_e32 v223, 1.0, v223
	v_add_f32_e32 v224, 1.0, v224
	v_add_f32_e32 v225, 1.0, v225
	v_add_f32_e32 v226, 1.0, v226
	v_add_f32_e32 v227, 1.0, v227
	v_rcp_f32_e32 v220, v220
	v_rcp_f32_e32 v221, v221
	v_rcp_f32_e32 v222, v222
	v_rcp_f32_e32 v223, v223
	v_rcp_f32_e32 v224, v224
	v_rcp_f32_e32 v225, v225
	v_rcp_f32_e32 v226, v226
	v_rcp_f32_e32 v227, v227
	v_mov_b32_e32 v15, v194
	v_mov_b32_e32 v10, v195
	v_mov_b32_e32 v14, v202
	v_mov_b32_e32 v11, v203
	v_mul_f32_e32 v204, v204, v220
	v_mul_f32_e32 v205, v205, v221
	v_mul_f32_e32 v206, v206, v222
	v_mul_f32_e32 v207, v207, v223
	v_mul_f32_e32 v208, v208, v224
	v_mul_f32_e32 v209, v209, v225
	v_mul_f32_e32 v210, v210, v226
	v_mul_f32_e32 v211, v211, v227
	v_mul_f32_e32 v212, v212, v204
	v_mul_f32_e32 v213, v213, v205
	v_mul_f32_e32 v214, v214, v206
	v_mul_f32_e32 v215, v215, v207
	v_mul_f32_e32 v216, v216, v208
	v_mul_f32_e32 v217, v217, v209
	v_mul_f32_e32 v218, v218, v210
	v_mul_f32_e32 v219, v219, v211
	v_cvt_pk_bf16_f32 v212, v212, v212
	v_cvt_pk_bf16_f32 v213, v213, v213
	v_cvt_pk_bf16_f32 v214, v214, v214
	v_cvt_pk_bf16_f32 v215, v215, v215
	v_cvt_pk_bf16_f32 v216, v216, v216
	v_cvt_pk_bf16_f32 v217, v217, v217
	v_cvt_pk_bf16_f32 v218, v218, v218
	v_cvt_pk_bf16_f32 v219, v219, v219
	v_cmp_lt_i32_e32 vcc, 0, v34
	s_and_b64 exec, exec, vcc
	global_store_short v24, v212, s[42:43]
	v_cmp_lt_i32_e32 vcc, 1, v34
	s_and_b64 exec, exec, vcc
	global_store_short v25, v213, s[42:43] offset:128
	v_cmp_lt_i32_e32 vcc, 2, v34
	s_and_b64 exec, exec, vcc
	global_store_short v26, v214, s[42:43] offset:256
	v_cmp_lt_i32_e32 vcc, 3, v34
	s_and_b64 exec, exec, vcc
	global_store_short v27, v215, s[42:43] offset:384
	v_cmp_lt_i32_e32 vcc, 4, v34
	s_and_b64 exec, exec, vcc
	global_store_short v28, v216, s[42:43] offset:512
	v_cmp_lt_i32_e32 vcc, 5, v34
	s_and_b64 exec, exec, vcc
	global_store_short v29, v217, s[42:43] offset:640
	v_cmp_lt_i32_e32 vcc, 6, v34
	s_and_b64 exec, exec, vcc
	global_store_short v30, v218, s[42:43] offset:768
	v_cmp_lt_i32_e32 vcc, 7, v34
	s_and_b64 exec, exec, vcc
	global_store_short v31, v219, s[42:43] offset:896
	s_mov_b64 exec, -1
	v_add_u32_e32 v17, 0x1020, v17
	v_add_u32_e32 v18, 8, v18
	s_sub_u32 s62, s62, 1
	s_cmp_lg_u32 s62, 0
	s_cbranch_scc1 .Lcv12_loop
	s_branch .LBB0_2363
